# shared hand-written grid barrier: one L2 write-back and one post-release L2 acquire per XCC, followers invalidate their L1 while waiting; shorter atomic chain
# speedup vs baseline: 1.0075x; 1.0075x over previous
_Z3fwd4Args:
	s_mov_b32 s101, 0
	s_load_dwordx2 s[4:5], s[0:1], 0xc8
	v_and_b32_e32 v1, 0x3ff, v0
	s_movk_i32 s3, 0x3ff
	v_readfirstlane_b32 s92, v1
	s_waitcnt lgkmcnt(0)
	v_writelane_b32 v252, s4, 0
	s_cmp_gt_i32 s4, -1
	s_nop 0
	v_writelane_b32 v252, s5, 1
	s_cbranch_scc1 .LBB0_12
	v_lshrrev_b32_e32 v2, 20, v0
	v_lshrrev_b32_e32 v0, 10, v0
	v_or_b32_e32 v0, v0, v2
	v_and_or_b32 v0, v0, s3, v1
	v_cmp_eq_u32_e32 vcc, 0, v0
	s_barrier
	s_and_saveexec_b64 s[4:5], vcc
	s_cbranch_execz .LBB0_11
	buffer_wbl2 sc1
	s_load_dwordx2 s[6:7], s[0:1], 0x128
	s_mov_b64 s[8:9], exec
	v_mbcnt_lo_u32_b32 v0, s8, 0
	v_mbcnt_hi_u32_b32 v0, s9, v0
	v_cmp_eq_u32_e32 vcc, 0, v0
	s_waitcnt lgkmcnt(0)
	s_load_dword s3, s[6:7], 0x28
	s_and_saveexec_b64 s[10:11], vcc
	s_cbranch_execz .LBB0_4
	s_bcnt1_i32_b64 s8, s[8:9]
	v_mov_b32_e32 v1, 0
	v_mov_b32_e32 v2, s8
	global_atomic_add v1, v1, v2, s[6:7] offset:32 sc0

.LBB0_219:
	s_waitcnt vmcnt(0)
	s_barrier
	s_mov_b64 s[4:5], s[4:5]
	s_mov_b32 s98, 1
	s_branch .Lxbar
.Lxbar_ret_1:
	s_waitcnt lgkmcnt(0)
	s_barrier

.LBB0_331:
	s_waitcnt vmcnt(0)
	s_barrier
	s_mov_b64 s[4:5], s[18:19]
	s_mov_b32 s98, 2
	s_branch .Lxbar

.LBB0_455:
	s_waitcnt vmcnt(0)
	s_waitcnt lgkmcnt(0)
	s_barrier
	s_mov_b64 s[4:5], s[14:15]
	s_mov_b32 s98, 3
	s_branch .Lxbar

.LBB0_569:
	s_waitcnt vmcnt(0)
	s_waitcnt lgkmcnt(0)
	s_barrier
	s_mov_b64 s[4:5], s[14:15]
	s_mov_b32 s98, 4
	s_branch .Lxbar

.LBB0_699:
	s_waitcnt vmcnt(0)
	s_waitcnt lgkmcnt(0)
	s_barrier
	s_mov_b64 s[4:5], s[10:11]
	s_mov_b32 s98, 5
	s_branch .Lxbar
.Lxbar_ret_5:
	s_branch .Lxbar_tail_5
.LBB0_750:
	s_add_u32 s0, s94, 0x800000
	v_writelane_b32 v254, s0, 48
	s_addc_u32 s0, s95, 0
	v_writelane_b32 v254, s0, 49
	s_add_u32 s0, s94, 0xd400000
	s_addc_u32 s1, s95, 0
	v_writelane_b32 v253, s0, 14
	s_movk_i32 s4, 0xc1
	v_readlane_b32 s12, v252, 32
	v_writelane_b32 v253, s1, 15
	s_add_u32 s0, s94, 0x13400000
	s_addc_u32 s1, s95, 0
	v_writelane_b32 v254, s0, 33
	v_readlane_b32 s18, v252, 18
	v_readlane_b32 s19, v252, 19
	v_writelane_b32 v254, s1, 34
	s_mov_b32 s25, 0x2aaaaaab
	v_readlane_b32 s28, v254, 12
	v_readlane_b32 s29, v254, 13
	s_and_b64 s[0:1], s[28:29], exec
	s_cselect_b32 s0, s4, 0xc0
	v_readlane_b32 s9, v254, 14
	s_mul_i32 s0, s0, s9
	v_readlane_b32 s8, v254, 15
	s_add_i32 s0, s0, s8
	s_mul_hi_i32 s1, s0, 0x2aaaaaab
	s_lshr_b32 s4, s1, 31
	s_ashr_i32 s1, s1, 4
	s_add_i32 s1, s1, s4
	s_lshl_b32 s4, s1, 2
	s_mulk_i32 s1, 0x60
	s_sub_i32 s1, s0, s1
	s_bfe_i32 s0, s1, 0x80000
	s_bfe_u32 s0, s0, 0x2000d
	s_add_i32 s5, s1, s0
	s_bfe_i32 s0, s5, 0x80000
	s_and_b32 s5, s5, 0xfc
	s_sub_i32 s1, s1, s5
	s_sext_i32_i16 s10, s0
	s_sext_i32_i8 s1, s1
	s_lshr_b32 s0, s10, 2
	s_add_i32 s16, s4, s1
	s_ashr_i32 s1, s10, 2
	v_writelane_b32 v254, s1, 50
	s_movk_i32 s1, 0x61
	s_and_b64 s[4:5], s[28:29], exec
	s_cselect_b32 s1, s1, 0x60
	s_mul_i32 s1, s1, s9
	s_add_i32 s1, s1, s8
	s_mul_hi_i32 s4, s1, 0x2aaaaaab
	s_lshr_b32 s5, s4, 31
	s_ashr_i32 s4, s4, 3
	s_add_i32 s4, s4, s5
	s_lshl_b32 s5, s4, 2
	s_mul_i32 s4, s4, 48
	s_sub_i32 s1, s1, s4
	s_bfe_i32 s4, s1, 0x80000
	s_bfe_u32 s4, s4, 0x2000d
	s_add_i32 s10, s1, s4
	s_bfe_i32 s4, s10, 0x80000
	s_and_b32 s10, s10, 0xfc
	s_sub_i32 s1, s1, s10
	s_sext_i32_i16 s11, s4
	s_sext_i32_i8 s1, s1
	s_add_i32 s20, s5, s1
	s_ashr_i32 s1, s11, 2
	v_writelane_b32 v253, s1, 10
	s_ashr_i32 s1, s96, 3
	s_mul_i32 s1, s1, s9
	s_add_i32 s10, s1, s8
	s_lshl_b32 s52, s12, 5
	v_readlane_b32 s1, v253, 18
	s_lshr_b32 s22, s1, 8
	s_and_b32 s1, s52, 0x60
	v_writelane_b32 v254, s1, 17
	s_lshl_b32 s1, s12, 7
	s_lshr_b32 s4, s11, 2
	s_add_i32 s51, s1, 0
	s_lshl_b32 s1, s22, 7
	s_or_b32 s11, s52, 0xffffff80
	s_add_i32 s1, s11, s1
	v_writelane_b32 v254, s1, 20
	s_lshl_b32 s1, s12, 12
	s_add_i32 s36, s1, 0
	s_and_b32 s5, s96, 7
	s_add_i32 s51, s51, 0x18000
	s_add_i32 s36, s36, 0x18400
	v_alignbit_b32 v0, 64, s9, 31
	s_cmpk_lt_i32 s18, 0x4000
	v_readfirstlane_b32 s1, v0
	s_cselect_b64 s[12:13], -1, 0
	s_mul_i32 s1, s1, s9
	v_writelane_b32 v253, s12, 12
	s_add_i32 s1, s1, s8
	s_lshl_b32 s11, s9, 5
	v_writelane_b32 v253, s13, 13
	s_ashr_i32 s12, s1, 31
	s_lshr_b32 s12, s12, 26
	s_add_i32 s12, s1, s12
	s_ashr_i32 s13, s12, 6
	s_lshl_b32 s13, s13, 2
	s_sub_i32 s14, 64, s13
	s_andn2_b32 s12, s12, 63
	s_min_i32 s14, s14, 4
	s_sub_i32 s12, s1, s12
	s_add_u32 s1, s94, 0x252000
	v_writelane_b32 v252, s1, 2
	s_addc_u32 s1, s95, 0
	s_add_u32 s26, s94, 0x80000
	s_addc_u32 s27, s95, 0
	v_writelane_b32 v253, s26, 1
	v_writelane_b32 v254, s1, 51
	s_add_u32 s1, s94, 0x8000
	v_writelane_b32 v253, s27, 2
	v_writelane_b32 v253, s1, 3
	s_addc_u32 s1, s95, 0
	v_writelane_b32 v254, s1, 47
	s_add_u32 s1, s94, 0x1f2000
	v_writelane_b32 v254, s1, 8
	s_addc_u32 s1, s95, 0
	v_writelane_b32 v254, s1, 10
	s_add_u32 s1, s94, 0x360000
	v_writelane_b32 v254, s1, 11
	s_addc_u32 s1, s95, 0
	v_writelane_b32 v254, s1, 23
	s_add_u32 s1, s94, 0x3c00000
	v_writelane_b32 v254, s1, 52
	s_addc_u32 s1, s95, 0
	v_writelane_b32 v254, s1, 53
	s_mov_b32 s6, s16
	s_ashr_i32 s17, s16, 31
	v_writelane_b32 v254, s6, 54
	s_lshl_b64 s[16:17], s[16:17], 19
	s_bfe_i64 s[0:1], s[0:1], 0x100000
	v_writelane_b32 v254, s7, 55
	v_writelane_b32 v254, s16, 56
	s_lshl_b64 s[0:1], s[0:1], 19
	s_ashr_i32 s21, s20, 31
	v_writelane_b32 v254, s17, 57
	v_writelane_b32 v254, s0, 58
	s_waitcnt lgkmcnt(0)
	v_cvt_f32_i32_e32 v1, s12
	s_mov_b32 s24, 10
	v_writelane_b32 v254, s1, 59
	s_mov_b32 s0, s20
	v_writelane_b32 v253, s0, 6
	v_mov_b32_e32 v236, 0x358637bd
	v_mov_b32_e32 v64, 0
	v_writelane_b32 v253, s1, 7
	s_lshl_b64 s[0:1], s[20:21], 19
	v_writelane_b32 v253, s0, 16
	v_mov_b32_e32 v234, 1
	v_mov_b32_e32 v235, 2
	v_writelane_b32 v253, s1, 17
	s_bfe_i64 s[0:1], s[4:5], 0x100000
	s_lshl_b64 s[0:1], s[0:1], 19
	s_cmp_eq_u32 s5, 0
	s_cselect_b32 s6, s10, s2
	v_writelane_b32 v254, s0, 35
	s_cmpk_lt_i32 s6, 0xc00
	s_mul_i32 s4, s9, 33
	v_writelane_b32 v254, s1, 36
	s_cselect_b64 s[0:1], -1, 0
	v_writelane_b32 v254, s0, 37
	s_bfe_u32 s15, s6, 0x30007
	s_ashr_i32 s92, s6, 10
	v_writelane_b32 v254, s1, 38
	s_lshr_b32 s0, s6, 8
	s_add_i32 s5, s0, s6
	s_and_b32 s10, s5, 7
	s_lshl_b32 s17, s10, 8
	s_and_b32 s16, s17, 0x100
	s_add_i32 s1, s17, 0xffffff80
	v_writelane_b32 v254, s1, 60
	s_lshr_b32 s1, s16, 1
	s_bfe_u32 s0, s6, 0x40003
	s_xor_b32 s1, s1, 0x80
	s_cmp_eq_u32 s10, 0
	v_writelane_b32 v254, s1, 61
	s_cselect_b32 s1, 0x80, 0
	v_writelane_b32 v254, s1, 62
	s_lshl_b32 s1, s92, 4
	s_or_b32 s0, s0, s1
	s_ashr_i32 s1, s0, 31
	s_lshl_b32 s19, s15, 18
	s_lshl_b64 s[0:1], s[0:1], 21
	v_writelane_b32 v254, s19, 63
	s_add_u32 s19, s0, 0x6000000
	v_writelane_b32 v254, s0, 39
	v_writelane_b32 v255, s19, 0
	v_mov_b32_e32 v237, 0xc0
	v_writelane_b32 v254, s1, 40
	s_addc_u32 s0, s1, 0
	v_writelane_b32 v255, s0, 1
	s_bfe_u32 s0, s5, 0x20001
	v_writelane_b32 v255, s0, 2
	s_add_i32 s0, s16, s52
	v_writelane_b32 v255, s0, 3
	v_writelane_b32 v255, s17, 4
	s_add_i32 s0, s17, s52
	v_writelane_b32 v255, s0, 5
	s_lshl_b32 s0, s10, 1
	s_add_i32 s0, s0, s22
	v_writelane_b32 v255, s0, 6
	s_lshl_b32 s0, s15, 11
	v_writelane_b32 v255, s0, 7
	s_and_b64 s[0:1], s[28:29], exec
	s_cselect_b32 s0, s4, s11
	s_add_i32 s0, s0, s8
	s_ashr_i32 s1, s0, 31
	s_lshr_b32 s1, s1, 28
	s_add_i32 s1, s0, s1
	s_ashr_i32 s4, s1, 4
	s_and_b32 s1, s1, 0xfff0
	s_sub_i32 s1, s0, s1
	s_bfe_i32 s0, s1, 0x80000
	s_bfe_u32 s0, s0, 0x2000d
	s_add_i32 s5, s1, s0
	s_bfe_i32 s0, s5, 0x80000
	s_and_b32 s5, s5, 0xfc
	s_sub_i32 s1, s1, s5
	s_lshl_b32 s4, s4, 2
	s_sext_i32_i8 s1, s1
	s_add_i32 s16, s4, s1
	s_sext_i32_i16 s10, s0
	s_ashr_i32 s17, s16, 31
	v_writelane_b32 v254, s22, 18
	s_lshr_b32 s0, s10, 2
	s_ashr_i32 s1, s10, 2
	s_lshl_b64 s[4:5], s[16:17], 19
	v_writelane_b32 v253, s1, 5
	v_writelane_b32 v254, s4, 41
	s_bfe_i64 s[0:1], s[0:1], 0x100000
	s_mov_b32 s10, s16
	v_writelane_b32 v254, s5, 42
	s_lshl_b64 s[4:5], s[0:1], 19
	v_writelane_b32 v253, s4, 18
	v_writelane_b32 v252, s10, 28
	s_lshl_b64 s[0:1], s[0:1], 21
	v_writelane_b32 v253, s5, 19
	s_sext_i32_i8 s4, s14
	v_cvt_f32_i32_e32 v0, s4
	v_writelane_b32 v252, s11, 29
	s_lshl_b64 s[10:11], s[16:17], 21
	v_writelane_b32 v254, s10, 15
	v_rcp_iflag_f32_e32 v2, v0
	v_mov_b32_e32 v240, 0xc1
	v_writelane_b32 v254, s11, 16
	v_writelane_b32 v254, s0, 12
	v_mul_f32_e32 v2, v1, v2
	v_trunc_f32_e32 v2, v2
	v_writelane_b32 v254, s1, 13
	s_xor_b32 s0, s12, s4
	v_fma_f32 v1, -v2, v0, v1
	v_cvt_i32_f32_e32 v2, v2
	s_ashr_i32 s0, s0, 30
	s_or_b32 s4, s0, 1
	v_cmp_ge_f32_e64 s[0:1], |v1|, |v0|
	s_and_b64 s[0:1], s[0:1], exec
	s_cselect_b32 s0, s4, 0
	v_readfirstlane_b32 s1, v2
	s_add_i32 s0, s1, s0
	s_sext_i32_i8 s1, s0
	s_mul_i32 s0, s0, s14
	s_sub_i32 s0, s12, s0
	s_sext_i32_i8 s0, s0
	v_writelane_b32 v255, s1, 8
	s_add_i32 s0, s13, s0
	v_writelane_b32 v255, s0, 9
	s_lshl_b32 s0, s6, 4
	v_writelane_b32 v255, s0, 10
	s_lshl_b32 s0, s96, 4
	v_writelane_b32 v254, s0, 27
	v_writelane_b32 v255, s6, 11
	s_add_i32 s0, s96, s6
	v_writelane_b32 v255, s0, 12
	v_readlane_b32 s0, v252, 20
	v_readlane_b32 s1, v252, 21
	s_mov_b32 s10, s0
	s_ashr_i32 s11, s0, 31
	s_mul_hi_i32 s1, s18, 0xc0
	s_mul_i32 s0, s18, 0xc0
	v_writelane_b32 v255, s0, 13
	s_mov_b32 s4, s18
	s_ashr_i32 s19, s18, 31
	v_writelane_b32 v255, s1, 14
	s_add_i32 s0, 0, 0x20000
	v_writelane_b32 v254, s0, 31
	s_add_i32 s0, 0, 0x27fc0
	v_writelane_b32 v254, s0, 25
	s_add_i32 s0, 0, 0x27fc4
	v_writelane_b32 v254, s0, 29
	s_add_i32 s0, 0, 0x21000
	v_writelane_b32 v255, s0, 15
	s_add_i32 s0, 0, 0x21400
	v_writelane_b32 v252, s4, 18
	v_writelane_b32 v255, s0, 16
	s_mul_hi_i32 s91, s10, 0xc0
	v_writelane_b32 v252, s5, 19
	s_lshl_b64 s[4:5], s[18:19], 11
	v_writelane_b32 v255, s4, 18
	s_mul_i32 s90, s10, 0xc0
	s_lshl_b64 s[62:63], s[10:11], 11
	v_writelane_b32 v255, s5, 19
	s_mov_b32 s4, s10
	v_writelane_b32 v252, s4, 20
	v_mov_b32_e32 v241, 0x7cf
	v_mov_b32_e32 v242, 0x60
	v_mov_b32_e32 v243, 0x61
	v_mov_b32_e32 v245, 0xf149f2ca
	v_mov_b64_e32 v[186:187], 0x100
	v_mov_b64_e32 v[188:189], 0xff
	s_movk_i32 s53, 0x600
	s_movk_i32 s50, 0x780
	s_movk_i32 s88, 0x7df
	s_movk_i32 s6, 0x7ef
	s_movk_i32 s26, 0x7ff
	s_movk_i32 s37, 0x7fff
	s_mov_b32 s0, 0
	v_writelane_b32 v252, s5, 21
	s_mov_b64 s[22:23], -1
	s_mov_b64 s[16:17], 0x80
	s_mov_b64 s[54:55], 0x300
	s_mov_b32 s18, 0x3e38aa3b
	s_mov_b64 s[20:21], 0x400
	s_mov_b32 s60, 0
	v_writelane_b32 v254, s92, 43
	s_mov_b64 s[8:9], s[90:91]
	s_mov_b64 s[14:15], s[62:63]
	v_writelane_b32 v255, s93, 20
	s_branch .LBB0_752

.LBB0_967:
	s_waitcnt vmcnt(0)
	s_barrier
	s_mov_b64 s[4:5], s[38:39]
	s_mov_b32 s98, 6
	s_branch .Lxbar

.LBB0_1124:
	s_waitcnt vmcnt(0)
	s_barrier
	s_mov_b64 s[4:5], s[38:39]
	s_mov_b32 s98, 7
	s_branch .Lxbar

.LBB0_1184:
	s_waitcnt vmcnt(0)
	s_barrier
	s_mov_b64 s[4:5], s[38:39]
	s_mov_b32 s98, 8
	s_branch .Lxbar

.LBB0_1280:
	s_waitcnt vmcnt(0)
	s_waitcnt lgkmcnt(0)
	s_barrier
	s_mov_b64 s[4:5], s[38:39]
	s_mov_b32 s98, 9
	s_branch .Lxbar

.LBB0_1394:
	s_waitcnt vmcnt(0)
	s_waitcnt lgkmcnt(0)
	s_barrier
	s_mov_b64 s[4:5], s[38:39]
	s_mov_b32 s98, 10
	s_branch .Lxbar

.LBB0_1562:
	s_waitcnt vmcnt(0)
	s_waitcnt lgkmcnt(0)
	s_barrier
	s_mov_b64 s[4:5], s[30:31]
	s_mov_b32 s98, 11
	s_branch .Lxbar

.LBB0_1613:
	s_endpgm

.Lxbar:
	s_add_u32 s101, s101, 1
	s_and_saveexec_b64 vcc, s[4:5]
	s_cbranch_execz .Lxbar_done
	v_mov_b32_e32 v0, 0x27fc0
	ds_read_b64 v[2:3], v0
	s_getreg_b32 s99, hwreg(HW_REG_XCC_ID, 0, 4)
	s_lshl_b32 s99, s99, 8
	s_add_u32 s100, s99, 0x1400
	v_mov_b32_e32 v1, s100
	s_add_u32 s100, s99, 0x4000
	v_mov_b32_e32 v7, s100
	s_add_u32 s100, s99, 0x5000
	v_mov_b32_e32 v8, s100
	v_mov_b32_e32 v4, 1
	global_atomic_add v5, v1, v4, s[94:95] sc0
	s_waitcnt vmcnt(0) lgkmcnt(0)
	v_readfirstlane_b32 s4, v2
	v_readfirstlane_b32 s5, v3
	v_readfirstlane_b32 s100, v5
	s_nop 3
	s_add_u32 s99, s101, 1
	s_mul_i32 s4, s4, s99
	s_mul_i32 s5, s5, s101
	s_add_u32 s100, s100, 1
	s_cmp_lg_u32 s100, s4
	s_cbranch_scc1 .Lxbar_follow
	buffer_wbl2 sc1
	s_waitcnt vmcnt(0) lgkmcnt(0)
	s_movk_i32 s99, 0x4000

	v_mov_b32_e32 v6, s99
	global_atomic_add v6, v4, s[94:95]
	s_addk_i32 s99, 0x100
	v_mov_b32_e32 v6, s99
	global_atomic_add v6, v4, s[94:95]
	s_addk_i32 s99, 0x100
	v_mov_b32_e32 v6, s99
	global_atomic_add v6, v4, s[94:95]
	s_addk_i32 s99, 0x100
	v_mov_b32_e32 v6, s99
	global_atomic_add v6, v4, s[94:95]
	s_addk_i32 s99, 0x100
	v_mov_b32_e32 v6, s99
	global_atomic_add v6, v4, s[94:95]
	s_addk_i32 s99, 0x100
	v_mov_b32_e32 v6, s99
	global_atomic_add v6, v4, s[94:95]
	s_addk_i32 s99, 0x100
	v_mov_b32_e32 v6, s99
	global_atomic_add v6, v4, s[94:95]
	s_addk_i32 s99, 0x100
	v_mov_b32_e32 v6, s99
	global_atomic_add v6, v4, s[94:95]
	s_addk_i32 s99, 0x100
	v_mov_b32_e32 v6, s99
	global_atomic_add v6, v4, s[94:95]
	s_addk_i32 s99, 0x100
	v_mov_b32_e32 v6, s99
	global_atomic_add v6, v4, s[94:95]
	s_addk_i32 s99, 0x100
	v_mov_b32_e32 v6, s99
	global_atomic_add v6, v4, s[94:95]
	s_addk_i32 s99, 0x100
	v_mov_b32_e32 v6, s99
	global_atomic_add v6, v4, s[94:95]
	s_addk_i32 s99, 0x100
	v_mov_b32_e32 v6, s99
	global_atomic_add v6, v4, s[94:95]
	s_addk_i32 s99, 0x100
	v_mov_b32_e32 v6, s99
	global_atomic_add v6, v4, s[94:95]
	s_addk_i32 s99, 0x100
	v_mov_b32_e32 v6, s99
	global_atomic_add v6, v4, s[94:95]
	s_addk_i32 s99, 0x100
	v_mov_b32_e32 v6, s99
	global_atomic_add v6, v4, s[94:95]
	s_mov_b32 s99, 0
.Lxbar_poll:
	global_load_dword v5, v7, s[94:95] sc1
	s_waitcnt vmcnt(0)
	v_readfirstlane_b32 s100, v5
	s_nop 3
	s_cmp_ge_u32 s100, s5
	s_cbranch_scc1 .Lxbar_rel
	s_sleep 1
	s_add_u32 s99, s99, 1
	s_cmp_lt_u32 s99, 0x400000
	s_cbranch_scc1 .Lxbar_poll
.Lxbar_rel:
	buffer_inv sc1
	s_waitcnt vmcnt(0)
	global_atomic_add v8, v4, s[94:95]
	s_branch .Lxbar_done
.Lxbar_follow:
	buffer_inv sc1
	s_mov_b32 s99, 0
.Lxbar_poll2:
	global_load_dword v5, v8, s[94:95] sc1
	s_waitcnt vmcnt(0)
	v_readfirstlane_b32 s100, v5
	s_nop 3
	s_cmp_ge_u32 s100, s101
	s_cbranch_scc1 .Lxbar_done
	s_sleep 1
	s_add_u32 s99, s99, 1
	s_cmp_lt_u32 s99, 0x400000
	s_cbranch_scc1 .Lxbar_poll2
.Lxbar_done:
	s_mov_b64 exec, vcc
	s_cmp_eq_u32 s98, 1
	s_cbranch_scc1 .Lxbar_ret_1
	s_cmp_eq_u32 s98, 2
	s_cbranch_scc1 .Lxbar_ret_2
	s_cmp_eq_u32 s98, 3
	s_cbranch_scc1 .Lxbar_ret_3
	s_cmp_eq_u32 s98, 4
	s_cbranch_scc1 .Lxbar_ret_4
	s_cmp_eq_u32 s98, 5
	s_cbranch_scc1 .Lxbar_ret_5
	s_cmp_eq_u32 s98, 6
	s_cbranch_scc1 .Lxbar_ret_6
	s_cmp_eq_u32 s98, 7
	s_cbranch_scc1 .Lxbar_ret_7
	s_cmp_eq_u32 s98, 8
	s_cbranch_scc1 .Lxbar_ret_8
	s_cmp_eq_u32 s98, 9
	s_cbranch_scc1 .Lxbar_ret_9
	s_cmp_eq_u32 s98, 10
	s_cbranch_scc1 .Lxbar_ret_10
	s_cmp_eq_u32 s98, 11
	s_cbranch_scc1 .Lxbar_ret_11
	s_endpgm

	.amdhsa_kernel _Z3fwd4Args
		.amdhsa_group_segment_fixed_size 0
		.amdhsa_private_segment_fixed_size 0
		.amdhsa_kernarg_size 464
		.amdhsa_user_sgpr_count 2
		.amdhsa_user_sgpr_dispatch_ptr 0
		.amdhsa_user_sgpr_queue_ptr 0
		.amdhsa_user_sgpr_kernarg_segment_ptr 1
		.amdhsa_user_sgpr_dispatch_id 0
		.amdhsa_user_sgpr_kernarg_preload_length 0
		.amdhsa_user_sgpr_kernarg_preload_offset 0
		.amdhsa_user_sgpr_private_segment_size 0
		.amdhsa_uses_dynamic_stack 0
		.amdhsa_enable_private_segment 0
		.amdhsa_system_sgpr_workgroup_id_x 1
		.amdhsa_system_sgpr_workgroup_id_y 0
		.amdhsa_system_sgpr_workgroup_id_z 0
		.amdhsa_system_sgpr_workgroup_info 0
		.amdhsa_system_vgpr_workitem_id 2
		.amdhsa_next_free_vgpr 256
		.amdhsa_next_free_sgpr 102
		.amdhsa_accum_offset 256
		.amdhsa_reserve_vcc 1
		.amdhsa_float_round_mode_32 0
		.amdhsa_float_round_mode_16_64 0
		.amdhsa_float_denorm_mode_32 3
		.amdhsa_float_denorm_mode_16_64 3
		.amdhsa_dx10_clamp 1
		.amdhsa_ieee_mode 1
		.amdhsa_fp16_overflow 0
		.amdhsa_tg_split 0
		.amdhsa_exception_fp_ieee_invalid_op 0
		.amdhsa_exception_fp_denorm_src 0
		.amdhsa_exception_fp_ieee_div_zero 0
		.amdhsa_exception_fp_ieee_overflow 0
		.amdhsa_exception_fp_ieee_underflow 0
		.amdhsa_exception_fp_ieee_inexact 0
		.amdhsa_exception_int_div_zero 0
	.end_amdhsa_kernel

amdhsa.kernels:
  - .agpr_count:     0
    .args:
      - .offset:         0
        .size:           208
        .value_kind:     by_value
      - .offset:         208
        .size:           4
        .value_kind:     hidden_block_count_x
      - .offset:         212
        .size:           4
        .value_kind:     hidden_block_count_y
      - .offset:         216
        .size:           4
        .value_kind:     hidden_block_count_z
      - .offset:         220
        .size:           2
        .value_kind:     hidden_group_size_x
      - .offset:         222
        .size:           2
        .value_kind:     hidden_group_size_y
      - .offset:         224
        .size:           2
        .value_kind:     hidden_group_size_z
      - .offset:         226
        .size:           2
        .value_kind:     hidden_remainder_x
      - .offset:         228
        .size:           2
        .value_kind:     hidden_remainder_y
      - .offset:         230
        .size:           2
        .value_kind:     hidden_remainder_z
      - .offset:         248
        .size:           8
        .value_kind:     hidden_global_offset_x
      - .offset:         256
        .size:           8
        .value_kind:     hidden_global_offset_y
      - .offset:         264
        .size:           8
        .value_kind:     hidden_global_offset_z
      - .offset:         272
        .size:           2
        .value_kind:     hidden_grid_dims
      - .offset:         296
        .size:           8
        .value_kind:     hidden_multigrid_sync_arg
      - .offset:         328
        .size:           4
        .value_kind:     hidden_dynamic_lds_size
    .group_segment_fixed_size: 0
    .kernarg_segment_align: 8
    .kernarg_segment_size: 464
    .language:       OpenCL C
    .language_version:
      - 2
      - 0
    .max_flat_workgroup_size: 512
    .name:           _Z3fwd4Args
    .private_segment_fixed_size: 0
    .sgpr_count:     108
    .sgpr_spill_count: 284
    .symbol:         _Z3fwd4Args.kd
    .uniform_work_group_size: 1
    .uses_dynamic_stack: false
    .vgpr_count:     256
    .vgpr_spill_count: 0
    .wavefront_size: 64
